# v29 + kv-latent GEMM transposed-V epilogue: 8 rstd loads hoisted, one wait
# baseline (speedup 1.0000x reference)
; #define PG8_STAGE(bufoff, gbase, voff) do { _Pragma("unroll") for (int _i = 0; _i < 2; ++_i) \
;         __builtin_amdgcn_global_load_lds((const unsigned*)((const char*)(gbase) + (voff)[_i]), (PG8_LAS unsigned*)(lds + (bufoff) + ldsw + _i * 8192), 16, 0, 0); } while (0)
; #define PG8_LDA(dst, b, h) do { _Pragma("unroll") for (int m = 0; m < 4; ++m) _Pragma("unroll") for (int k = 0; k < 2; ++k) dst[m][k] = *(const PG8_LAS bf16x8*)(lds + PG8_SA(b, h) + aoff + m * 2048 + k * 1024); } while (0)
; #define PG8_LDB(dst, b, h) do { _Pragma("unroll") for (int n = 0; n < 2; ++n) _Pragma("unroll") for (int k = 0; k < 2; ++k) dst[n][k] = *(const PG8_LAS bf16x8*)(lds + PG8_SB(b, h) + boff + n * 2048 + k * 1024); } while (0)
; #define PG8_MMA(ai, bj, At, Bt) do { __builtin_amdgcn_s_setprio(1); _Pragma("unroll") for (int m = 0; m < 4; ++m) _Pragma("unroll") for (int n = 0; n < 2; ++n) _Pragma("unroll") for (int k = 0; k < 2; ++k) \
;         acc[ai][bj][m][n] = __builtin_amdgcn_mfma_f32_16x16x32_bf16(Bt[n][k], At[m][k], acc[ai][bj][m][n], 0, 0, 0); __builtin_amdgcn_s_setprio(0); } while (0)
; #define PG8_BAR __builtin_amdgcn_s_barrier()
; template <class Epi, class Sched, bool ALIGN_EPI = false, bool SP2 = false>
; __device__ __forceinline__ void gemm_phase(PG8_LAS unsigned char* lds, const Gemm g, const Sched& S, const Epi& E) {
;     ...
;             if constexpr (SP2) {
;             PG8_LDB(B0, 0, 0); PG8_LDB(B1, 0, 1); PG8_SCHED; PG8_LDA(At, 0, 0); PG8_STAGE(PG8_SA(1, 1), a1 + hstep, voffA);
;             PG8_WAIT_V(8); PG8_WAIT_L(0); PG8_BAR; PG8_MMA(0, 0, At, B0); PG8_MMA(0, 1, At, B1); PG8_BAR; PG8_SCHED;
;             PG8_LDA(At, 0, 1); PG8_STAGE(PG8_SB(0, 0), b2, voffB); PG8_STAGE(PG8_SB(0, 1), b2 + hstep, voffB); PG8_STAGE(PG8_SA(0, 0), a2, voffA);
;             PG8_WAIT_V(8); PG8_WAIT_L(0); PG8_BAR; PG8_MMA(1, 0, At, B0); PG8_MMA(1, 1, At, B1); PG8_BAR; PG8_SCHED;
;             PG8_LDB(B0, 1, 0); PG8_LDB(B1, 1, 1); PG8_SCHED; PG8_LDA(At, 1, 0); PG8_STAGE(PG8_SA(0, 1), a2 + hstep, voffA);
;             PG8_WAIT_V(8); PG8_WAIT_L(0); PG8_BAR; PG8_MMA(0, 0, At, B0); PG8_MMA(0, 1, At, B1); PG8_BAR; PG8_SCHED;
;             PG8_LDA(At, 1, 1); PG8_STAGE(PG8_SB(1, 0), b3, voffB); PG8_STAGE(PG8_SB(1, 1), b3 + hstep, voffB); PG8_STAGE(PG8_SA(1, 0), a3, voffA);
;             PG8_WAIT_V(8); PG8_WAIT_L(0); PG8_BAR; PG8_MMA(1, 0, At, B0); PG8_MMA(1, 1, At, B1); PG8_BAR; PG8_SCHED;
.LBB0_933:
	s_add_u32 s30, s22, s24
	s_addc_u32 s31, s23, s25
	s_add_u32 s28, s30, 0x100
	s_addc_u32 s29, s31, 0
	s_and_b64 s[26:27], s[14:15], exec
	s_cselect_b32 s27, s7, s29
	s_cselect_b32 s26, s56, s28
	s_add_u32 s24, s18, s24
	s_addc_u32 s25, s19, s25
	s_add_u32 s24, s24, 0x100
	s_addc_u32 s25, s25, 0
	s_add_i32 s66, 0, 0x10000
	s_and_b64 s[14:15], s[14:15], exec
	s_cselect_b32 s29, s5, s25
	s_cselect_b32 s28, s57, s24
	s_add_i32 s15, 0, 0x14000
	s_add_u32 s34, s30, 0x10080
	s_addc_u32 s35, s31, 0
	s_add_i32 s65, s66, s46
	s_add_i32 m0, s17, 0xc000
	s_add_i32 s68, s17, 0xe000
	s_add_i32 s62, s65, 0x2000
	v_add_u32_e32 v0, s66, v153
	s_add_u32 s30, s28, 0x10000
	ds_read_b128 v[140:143], v0
	ds_read_b128 v[144:147], v0 offset:1024
	ds_read_b128 v[148:151], v0 offset:2048
	ds_read_b128 v[156:159], v0 offset:3072
	v_add_u32_e32 v0, s15, v153
	s_addc_u32 s31, s29, 0
	s_add_i32 s64, s15, s46
	ds_read_b128 v[176:179], v0
	ds_read_b128 v[180:183], v0 offset:1024
	ds_read_b128 v[184:187], v0 offset:2048
	ds_read_b128 v[188:191], v0 offset:3072
	s_add_i32 s63, s64, 0x2000
	s_add_i32 s61, 0, 0x18000
	s_add_i32 s60, 0, 0x1c000
	s_add_u32 s24, s26, 0x10000
	s_addc_u32 s25, s27, 0
	s_add_i32 s59, s61, s46
	s_add_i32 s58, s59, 0x2000
	s_add_u32 s14, s28, 0x10080
	s_addc_u32 s15, s29, 0
	s_add_i32 s67, s60, s46
	s_add_i32 s66, s67, 0x2000
	v_lshl_add_u64 v[160:161], s[34:35], 0, v[130:131]
	ds_read_b128 v[192:195], v155
	ds_read_b128 v[196:199], v155 offset:1024
	ds_read_b128 v[200:203], v155 offset:2048
	ds_read_b128 v[204:207], v155 offset:3072
	ds_read_b128 v[224:227], v155 offset:4096
	ds_read_b128 v[228:231], v155 offset:5120
	ds_read_b128 v[232:235], v155 offset:6144
	ds_read_b128 v[236:239], v155 offset:7168
	global_load_lds_dwordx4 v[160:161], off
	v_lshl_add_u64 v[160:161], s[34:35], 0, v[134:135]
	s_mov_b32 m0, s68
	s_nop 0
	global_load_lds_dwordx4 v[160:161], off
	s_waitcnt vmcnt(8)
	s_waitcnt lgkmcnt(0)
	s_barrier
	s_setprio 1
	s_waitcnt lgkmcnt(0)
	v_mfma_f32_16x16x32_bf16 v[126:129], v[140:143], v[192:195], v[126:129]
	v_mfma_f32_16x16x32_bf16 v[122:125], v[148:151], v[192:195], v[122:125]
	v_mfma_f32_16x16x32_bf16 v[110:113], v[140:143], v[200:203], v[110:113]
	v_mfma_f32_16x16x32_bf16 v[106:109], v[148:151], v[200:203], v[106:109]
	v_mfma_f32_16x16x32_bf16 v[94:97], v[140:143], v[224:227], v[94:97]
	v_mfma_f32_16x16x32_bf16 v[90:93], v[148:151], v[224:227], v[90:93]
	v_mfma_f32_16x16x32_bf16 v[78:81], v[140:143], v[232:235], v[78:81]
	v_mfma_f32_16x16x32_bf16 v[74:77], v[148:151], v[232:235], v[74:77]
	v_mfma_f32_16x16x32_bf16 v[126:129], v[144:147], v[196:199], v[126:129]
	v_mfma_f32_16x16x32_bf16 v[122:125], v[156:159], v[196:199], v[122:125]
	v_mfma_f32_16x16x32_bf16 v[110:113], v[144:147], v[204:207], v[110:113]
	v_mfma_f32_16x16x32_bf16 v[106:109], v[156:159], v[204:207], v[106:109]
	v_mfma_f32_16x16x32_bf16 v[94:97], v[144:147], v[228:231], v[94:97]
	v_mfma_f32_16x16x32_bf16 v[90:93], v[156:159], v[228:231], v[90:93]
	v_mfma_f32_16x16x32_bf16 v[78:81], v[144:147], v[236:239], v[78:81]
	v_mfma_f32_16x16x32_bf16 v[74:77], v[156:159], v[236:239], v[74:77]
	s_setprio 0
	s_setprio 1
	v_mfma_f32_16x16x32_bf16 v[118:121], v[176:179], v[192:195], v[118:121]
	v_mfma_f32_16x16x32_bf16 v[114:117], v[184:187], v[192:195], v[114:117]
	v_mfma_f32_16x16x32_bf16 v[102:105], v[176:179], v[200:203], v[102:105]
	v_mfma_f32_16x16x32_bf16 v[98:101], v[184:187], v[200:203], v[98:101]
	v_mfma_f32_16x16x32_bf16 v[86:89], v[176:179], v[224:227], v[86:89]
	v_mfma_f32_16x16x32_bf16 v[82:85], v[184:187], v[224:227], v[82:85]
	v_mfma_f32_16x16x32_bf16 v[70:73], v[176:179], v[232:235], v[70:73]
	v_mfma_f32_16x16x32_bf16 v[66:69], v[184:187], v[232:235], v[66:69]
	v_mfma_f32_16x16x32_bf16 v[118:121], v[180:183], v[196:199], v[118:121]
	v_mfma_f32_16x16x32_bf16 v[114:117], v[188:191], v[196:199], v[114:117]
	v_mfma_f32_16x16x32_bf16 v[102:105], v[180:183], v[204:207], v[102:105]
	v_mfma_f32_16x16x32_bf16 v[98:101], v[188:191], v[204:207], v[98:101]
	v_mfma_f32_16x16x32_bf16 v[86:89], v[180:183], v[228:231], v[86:89]
	v_mfma_f32_16x16x32_bf16 v[82:85], v[188:191], v[228:231], v[82:85]
	v_mfma_f32_16x16x32_bf16 v[70:73], v[180:183], v[236:239], v[70:73]
	v_mfma_f32_16x16x32_bf16 v[66:69], v[188:191], v[236:239], v[66:69]
	s_setprio 0
	s_barrier
	s_mov_b32 m0, s65
	v_lshl_add_u64 v[160:161], s[28:29], 0, v[132:133]
	ds_read_b128 v[192:195], v155 offset:16384
	ds_read_b128 v[196:199], v155 offset:17408
	ds_read_b128 v[200:203], v155 offset:18432
	ds_read_b128 v[204:207], v155 offset:19456
	ds_read_b128 v[224:227], v155 offset:20480
	ds_read_b128 v[228:231], v155 offset:21504
	ds_read_b128 v[232:235], v155 offset:22528
	ds_read_b128 v[236:239], v155 offset:23552
	global_load_lds_dwordx4 v[160:161], off
	v_lshl_add_u64 v[214:215], s[28:29], 0, v[136:137]
	s_mov_b32 m0, s62
	v_lshl_add_u64 v[240:241], s[30:31], 0, v[132:133]
	global_load_lds_dwordx4 v[214:215], off
	s_mov_b32 m0, s64
	v_lshl_add_u64 v[242:243], s[26:27], 0, v[134:135]
	global_load_lds_dwordx4 v[240:241], off
	v_lshl_add_u64 v[240:241], s[30:31], 0, v[136:137]
	s_mov_b32 m0, s63
	s_nop 0
	global_load_lds_dwordx4 v[240:241], off
	v_lshl_add_u64 v[240:241], s[26:27], 0, v[130:131]
	s_mov_b32 m0, s17
	s_nop 0
	global_load_lds_dwordx4 v[240:241], off
	s_mov_b32 m0, s47
	s_nop 0
	global_load_lds_dwordx4 v[242:243], off
	s_waitcnt vmcnt(8)
	s_waitcnt lgkmcnt(0)
	s_barrier
; #define PG8_STAGE(bufoff, gbase, voff) do { _Pragma("unroll") for (int _i = 0; _i < 2; ++_i) \
;         __builtin_amdgcn_global_load_lds((const unsigned*)((const char*)(gbase) + (voff)[_i]), (PG8_LAS unsigned*)(lds + (bufoff) + ldsw + _i * 8192), 16, 0, 0); } while (0)
; #define PG8_LDA(dst, b, h) do { _Pragma("unroll") for (int m = 0; m < 4; ++m) _Pragma("unroll") for (int k = 0; k < 2; ++k) dst[m][k] = *(const PG8_LAS bf16x8*)(lds + PG8_SA(b, h) + aoff + m * 2048 + k * 1024); } while (0)
; #define PG8_LDB(dst, b, h) do { _Pragma("unroll") for (int n = 0; n < 2; ++n) _Pragma("unroll") for (int k = 0; k < 2; ++k) dst[n][k] = *(const PG8_LAS bf16x8*)(lds + PG8_SB(b, h) + boff + n * 2048 + k * 1024); } while (0)
; #define PG8_MMA(ai, bj, At, Bt) do { __builtin_amdgcn_s_setprio(1); _Pragma("unroll") for (int m = 0; m < 4; ++m) _Pragma("unroll") for (int n = 0; n < 2; ++n) _Pragma("unroll") for (int k = 0; k < 2; ++k) \
;         acc[ai][bj][m][n] = __builtin_amdgcn_mfma_f32_16x16x32_bf16(Bt[n][k], At[m][k], acc[ai][bj][m][n], 0, 0, 0); __builtin_amdgcn_s_setprio(0); } while (0)
; #define PG8_BAR __builtin_amdgcn_s_barrier()
; template <class Epi, class Sched, bool ALIGN_EPI = false, bool SP2 = false>
; __device__ __forceinline__ void gemm_phase(PG8_LAS unsigned char* lds, const Gemm g, const Sched& S, const Epi& E) {
;     ...
;             if constexpr (SP2) {
;             PG8_LDB(B0, 0, 0); PG8_LDB(B1, 0, 1); PG8_SCHED; PG8_LDA(At, 0, 0); PG8_STAGE(PG8_SA(1, 1), a1 + hstep, voffA);
;             PG8_WAIT_V(8); PG8_WAIT_L(0); PG8_BAR; PG8_MMA(0, 0, At, B0); PG8_MMA(0, 1, At, B1); PG8_BAR; PG8_SCHED;
;             PG8_LDA(At, 0, 1); PG8_STAGE(PG8_SB(0, 0), b2, voffB); PG8_STAGE(PG8_SB(0, 1), b2 + hstep, voffB); PG8_STAGE(PG8_SA(0, 0), a2, voffA);
;             PG8_WAIT_V(8); PG8_WAIT_L(0); PG8_BAR; PG8_MMA(1, 0, At, B0); PG8_MMA(1, 1, At, B1); PG8_BAR; PG8_SCHED;
;             PG8_LDB(B0, 1, 0); PG8_LDB(B1, 1, 1); PG8_SCHED; PG8_LDA(At, 1, 0); PG8_STAGE(PG8_SA(0, 1), a2 + hstep, voffA);
;             PG8_WAIT_V(8); PG8_WAIT_L(0); PG8_BAR; PG8_MMA(0, 0, At, B0); PG8_MMA(0, 1, At, B1); PG8_BAR; PG8_SCHED;
;             PG8_LDA(At, 1, 1); PG8_STAGE(PG8_SB(1, 0), b3, voffB); PG8_STAGE(PG8_SB(1, 1), b3 + hstep, voffB); PG8_STAGE(PG8_SA(1, 0), a3, voffA);
;             PG8_WAIT_V(8); PG8_WAIT_L(0); PG8_BAR; PG8_MMA(1, 0, At, B0); PG8_MMA(1, 1, At, B1); PG8_BAR; PG8_SCHED;
	s_setprio 1
	s_waitcnt lgkmcnt(0)
	v_mfma_f32_16x16x32_bf16 v[62:65], v[140:143], v[192:195], v[62:65]
	v_mfma_f32_16x16x32_bf16 v[58:61], v[148:151], v[192:195], v[58:61]
	v_mfma_f32_16x16x32_bf16 v[46:49], v[140:143], v[200:203], v[46:49]
	v_mfma_f32_16x16x32_bf16 v[42:45], v[148:151], v[200:203], v[42:45]
	v_mfma_f32_16x16x32_bf16 v[30:33], v[140:143], v[224:227], v[30:33]
	v_mfma_f32_16x16x32_bf16 v[26:29], v[148:151], v[224:227], v[26:29]
	v_mfma_f32_16x16x32_bf16 v[14:17], v[140:143], v[232:235], v[14:17]
	v_mfma_f32_16x16x32_bf16 v[10:13], v[148:151], v[232:235], v[10:13]
	v_mfma_f32_16x16x32_bf16 v[62:65], v[144:147], v[196:199], v[62:65]
	v_mfma_f32_16x16x32_bf16 v[58:61], v[156:159], v[196:199], v[58:61]
	v_mfma_f32_16x16x32_bf16 v[46:49], v[144:147], v[204:207], v[46:49]
	v_mfma_f32_16x16x32_bf16 v[42:45], v[156:159], v[204:207], v[42:45]
	v_mfma_f32_16x16x32_bf16 v[30:33], v[144:147], v[228:231], v[30:33]
	v_mfma_f32_16x16x32_bf16 v[26:29], v[156:159], v[228:231], v[26:29]
	v_mfma_f32_16x16x32_bf16 v[14:17], v[144:147], v[236:239], v[14:17]
	v_mfma_f32_16x16x32_bf16 v[10:13], v[156:159], v[236:239], v[10:13]
	s_setprio 0
	s_setprio 1
	v_mfma_f32_16x16x32_bf16 v[54:57], v[176:179], v[192:195], v[54:57]
	v_mfma_f32_16x16x32_bf16 v[50:53], v[184:187], v[192:195], v[50:53]
	v_mfma_f32_16x16x32_bf16 v[38:41], v[176:179], v[200:203], v[38:41]
	v_mfma_f32_16x16x32_bf16 v[34:37], v[184:187], v[200:203], v[34:37]
	v_mfma_f32_16x16x32_bf16 v[22:25], v[176:179], v[224:227], v[22:25]
	v_mfma_f32_16x16x32_bf16 v[18:21], v[184:187], v[224:227], v[18:21]
	v_mfma_f32_16x16x32_bf16 v[6:9], v[176:179], v[232:235], v[6:9]
	v_mfma_f32_16x16x32_bf16 v[2:5], v[184:187], v[232:235], v[2:5]
	v_mfma_f32_16x16x32_bf16 v[54:57], v[180:183], v[196:199], v[54:57]
	v_mfma_f32_16x16x32_bf16 v[50:53], v[188:191], v[196:199], v[50:53]
	v_mfma_f32_16x16x32_bf16 v[38:41], v[180:183], v[204:207], v[38:41]
	v_mfma_f32_16x16x32_bf16 v[34:37], v[188:191], v[204:207], v[34:37]
	v_mfma_f32_16x16x32_bf16 v[22:25], v[180:183], v[228:231], v[22:25]
	v_mfma_f32_16x16x32_bf16 v[18:21], v[188:191], v[228:231], v[18:21]
	v_mfma_f32_16x16x32_bf16 v[6:9], v[180:183], v[236:239], v[6:9]
	v_mfma_f32_16x16x32_bf16 v[2:5], v[188:191], v[236:239], v[2:5]
	s_setprio 0
	s_barrier
	v_add_u32_e32 v0, s61, v153
	ds_read_b128 v[140:143], v0
	ds_read_b128 v[144:147], v0 offset:1024
	ds_read_b128 v[148:151], v0 offset:2048
	ds_read_b128 v[156:159], v0 offset:3072
	v_add_u32_e32 v0, s60, v153
	ds_read_b128 v[176:179], v0
	ds_read_b128 v[180:183], v0 offset:1024
	ds_read_b128 v[184:187], v0 offset:2048
	ds_read_b128 v[188:191], v0 offset:3072
	s_mov_b32 m0, s48
	v_lshl_add_u64 v[244:245], s[24:25], 0, v[130:131]
	ds_read_b128 v[192:195], v155 offset:32768
	ds_read_b128 v[196:199], v155 offset:33792
	ds_read_b128 v[200:203], v155 offset:34816
	ds_read_b128 v[204:207], v155 offset:35840
	ds_read_b128 v[224:227], v155 offset:36864
	ds_read_b128 v[228:231], v155 offset:37888
	ds_read_b128 v[232:235], v155 offset:38912
	ds_read_b128 v[236:239], v155 offset:39936
	global_load_lds_dwordx4 v[244:245], off
	v_lshl_add_u64 v[244:245], s[24:25], 0, v[134:135]
	s_mov_b32 m0, s49
	s_nop 0
	global_load_lds_dwordx4 v[244:245], off
	s_waitcnt vmcnt(8)
	s_waitcnt lgkmcnt(0)
	s_barrier
	s_setprio 1
	s_waitcnt lgkmcnt(0)
	v_mfma_f32_16x16x32_bf16 v[126:129], v[140:143], v[192:195], v[126:129]
	v_mfma_f32_16x16x32_bf16 v[122:125], v[148:151], v[192:195], v[122:125]
	v_mfma_f32_16x16x32_bf16 v[110:113], v[140:143], v[200:203], v[110:113]
	v_mfma_f32_16x16x32_bf16 v[106:109], v[148:151], v[200:203], v[106:109]
	v_mfma_f32_16x16x32_bf16 v[94:97], v[140:143], v[224:227], v[94:97]
	v_mfma_f32_16x16x32_bf16 v[90:93], v[148:151], v[224:227], v[90:93]
	v_mfma_f32_16x16x32_bf16 v[78:81], v[140:143], v[232:235], v[78:81]
	v_mfma_f32_16x16x32_bf16 v[74:77], v[148:151], v[232:235], v[74:77]
	v_mfma_f32_16x16x32_bf16 v[126:129], v[144:147], v[196:199], v[126:129]
	v_mfma_f32_16x16x32_bf16 v[122:125], v[156:159], v[196:199], v[122:125]
	v_mfma_f32_16x16x32_bf16 v[110:113], v[144:147], v[204:207], v[110:113]
	v_mfma_f32_16x16x32_bf16 v[106:109], v[156:159], v[204:207], v[106:109]
	v_mfma_f32_16x16x32_bf16 v[94:97], v[144:147], v[228:231], v[94:97]
	v_mfma_f32_16x16x32_bf16 v[90:93], v[156:159], v[228:231], v[90:93]
	v_mfma_f32_16x16x32_bf16 v[78:81], v[144:147], v[236:239], v[78:81]
	v_mfma_f32_16x16x32_bf16 v[74:77], v[156:159], v[236:239], v[74:77]
	s_setprio 0
	s_setprio 1
	v_mfma_f32_16x16x32_bf16 v[118:121], v[176:179], v[192:195], v[118:121]
	v_mfma_f32_16x16x32_bf16 v[114:117], v[184:187], v[192:195], v[114:117]
	v_mfma_f32_16x16x32_bf16 v[102:105], v[176:179], v[200:203], v[102:105]
	v_mfma_f32_16x16x32_bf16 v[98:101], v[184:187], v[200:203], v[98:101]
	v_mfma_f32_16x16x32_bf16 v[86:89], v[176:179], v[224:227], v[86:89]
	v_mfma_f32_16x16x32_bf16 v[82:85], v[184:187], v[224:227], v[82:85]
	v_mfma_f32_16x16x32_bf16 v[70:73], v[176:179], v[232:235], v[70:73]
	v_mfma_f32_16x16x32_bf16 v[66:69], v[184:187], v[232:235], v[66:69]
	v_mfma_f32_16x16x32_bf16 v[118:121], v[180:183], v[196:199], v[118:121]
	v_mfma_f32_16x16x32_bf16 v[114:117], v[188:191], v[196:199], v[114:117]
	v_mfma_f32_16x16x32_bf16 v[102:105], v[180:183], v[204:207], v[102:105]
	v_mfma_f32_16x16x32_bf16 v[98:101], v[188:191], v[204:207], v[98:101]
	v_mfma_f32_16x16x32_bf16 v[86:89], v[180:183], v[228:231], v[86:89]
	v_mfma_f32_16x16x32_bf16 v[82:85], v[188:191], v[228:231], v[82:85]
	v_mfma_f32_16x16x32_bf16 v[70:73], v[180:183], v[236:239], v[70:73]
	v_mfma_f32_16x16x32_bf16 v[66:69], v[188:191], v[236:239], v[66:69]
	s_setprio 0
	s_barrier
; __device__ __forceinline__ bf16_t f2bf(float x) { return (bf16_t)(pk2(x, 0.f) & 0xffffu); }
; #define PG8_WAIT_V(n) asm volatile("s_waitcnt vmcnt(" #n ")" ::: "memory")
; #define PG8_BAR __builtin_amdgcn_s_barrier()
; template <class Epi, class Sched, bool ALIGN_EPI = false, bool SP2 = false>
; __device__ __forceinline__ void gemm_phase(PG8_LAS unsigned char* lds, const Gemm g, const Sched& S, const Epi& E) {
;     ...
;             if constexpr (SP2) {
;             PG8_LDB(B0, 0, 0); PG8_LDB(B1, 0, 1); PG8_SCHED; PG8_LDA(At, 0, 0); PG8_STAGE(PG8_SA(1, 1), a1 + hstep, voffA);
;             PG8_WAIT_V(8); PG8_WAIT_L(0); PG8_BAR; PG8_MMA(0, 0, At, B0); PG8_MMA(0, 1, At, B1); PG8_BAR; PG8_SCHED;
;             PG8_LDA(At, 0, 1); PG8_STAGE(PG8_SB(0, 0), b2, voffB); PG8_STAGE(PG8_SB(0, 1), b2 + hstep, voffB); PG8_STAGE(PG8_SA(0, 0), a2, voffA);
;             PG8_WAIT_V(8); PG8_WAIT_L(0); PG8_BAR; PG8_MMA(1, 0, At, B0); PG8_MMA(1, 1, At, B1); PG8_BAR; PG8_SCHED;
;             PG8_LDB(B0, 1, 0); PG8_LDB(B1, 1, 1); PG8_SCHED; PG8_LDA(At, 1, 0); PG8_STAGE(PG8_SA(0, 1), a2 + hstep, voffA);
;             PG8_WAIT_V(8); PG8_WAIT_L(0); PG8_BAR; PG8_MMA(0, 0, At, B0); PG8_MMA(0, 1, At, B1); PG8_BAR; PG8_SCHED;
;             PG8_LDA(At, 1, 1); PG8_STAGE(PG8_SB(1, 0), b3, voffB); PG8_STAGE(PG8_SB(1, 1), b3 + hstep, voffB); PG8_STAGE(PG8_SA(1, 0), a3, voffA);
;             PG8_WAIT_V(8); PG8_WAIT_L(0); PG8_BAR; PG8_MMA(1, 0, At, B0); PG8_MMA(1, 1, At, B1); PG8_BAR; PG8_SCHED;
;     __device__ __forceinline__ void operator()(AccRef acc, const pg8::Unit& u, int wr, int wc, int fr, int fq) const {
;     ...
;         } else if (WHICH == 1) {
;             bf16_t* VT = (bf16_t*)(ws + WS_VAT); const int h0 = (pn - 4) * 2;
; #pragma unroll
;             for (int ai = 0; ai < 2; ++ai)
; #pragma unroll
;                 for (int m = 0; m < 4; ++m) { const int row = row0 + ai * 128 + m * 16; const int b = row >> 11, s = row & 2047; const float rs = rstd(row);
; #pragma unroll
;                     for (int bj = 0; bj < 2; ++bj) { const unsigned po = (unsigned)(((b * 8 + h0 + bj) * 128 + cl0) * 2048 + s);
; #pragma unroll
;                         for (int n = 0; n < 2; ++n)
; #pragma unroll
;                             for (int j = 0; j < 4; ++j) VT[po + (unsigned)((4 * n + j) * 2048)] = f2bf(acc[ai][bj][m][n][j] * rs); }
;                     asm volatile("" ::: "memory"); }
	s_mov_b32 m0, s59
	v_lshl_add_u64 v[160:161], v[160:161], 0, s[20:21]
	ds_read_b128 v[192:195], v155 offset:49152
	ds_read_b128 v[196:199], v155 offset:50176
	ds_read_b128 v[200:203], v155 offset:51200
	ds_read_b128 v[204:207], v155 offset:52224
	ds_read_b128 v[224:227], v155 offset:53248
	ds_read_b128 v[228:231], v155 offset:54272
	ds_read_b128 v[232:235], v155 offset:55296
	ds_read_b128 v[236:239], v155 offset:56320
	global_load_lds_dwordx4 v[160:161], off
	v_lshl_add_u64 v[160:161], v[214:215], 0, s[20:21]
	s_mov_b32 m0, s58
	s_nop 0
	global_load_lds_dwordx4 v[160:161], off
	v_lshl_add_u64 v[160:161], s[14:15], 0, v[132:133]
	s_mov_b32 m0, s67
	s_nop 0
	global_load_lds_dwordx4 v[160:161], off
	v_lshl_add_u64 v[160:161], s[14:15], 0, v[136:137]
	s_mov_b32 m0, s66
	s_nop 0
	global_load_lds_dwordx4 v[160:161], off
	v_lshl_add_u64 v[160:161], v[240:241], 0, s[20:21]
	s_mov_b32 m0, s51
	s_nop 0
	global_load_lds_dwordx4 v[160:161], off
	v_lshl_add_u64 v[160:161], v[242:243], 0, s[20:21]
	s_mov_b32 m0, s52
	s_nop 0
	global_load_lds_dwordx4 v[160:161], off
	s_waitcnt vmcnt(8)
	s_waitcnt lgkmcnt(0)
	s_barrier
	s_setprio 1
	s_waitcnt lgkmcnt(0)
	v_mfma_f32_16x16x32_bf16 v[62:65], v[140:143], v[192:195], v[62:65]
	v_mfma_f32_16x16x32_bf16 v[58:61], v[148:151], v[192:195], v[58:61]
	v_mfma_f32_16x16x32_bf16 v[46:49], v[140:143], v[200:203], v[46:49]
	v_mfma_f32_16x16x32_bf16 v[42:45], v[148:151], v[200:203], v[42:45]
	v_mfma_f32_16x16x32_bf16 v[30:33], v[140:143], v[224:227], v[30:33]
	v_mfma_f32_16x16x32_bf16 v[26:29], v[148:151], v[224:227], v[26:29]
	v_mfma_f32_16x16x32_bf16 v[14:17], v[140:143], v[232:235], v[14:17]
	v_mfma_f32_16x16x32_bf16 v[10:13], v[148:151], v[232:235], v[10:13]
	v_mfma_f32_16x16x32_bf16 v[62:65], v[144:147], v[196:199], v[62:65]
	v_mfma_f32_16x16x32_bf16 v[58:61], v[156:159], v[196:199], v[58:61]
	v_mfma_f32_16x16x32_bf16 v[46:49], v[144:147], v[204:207], v[46:49]
	v_mfma_f32_16x16x32_bf16 v[42:45], v[156:159], v[204:207], v[42:45]
	v_mfma_f32_16x16x32_bf16 v[30:33], v[144:147], v[228:231], v[30:33]
	v_mfma_f32_16x16x32_bf16 v[26:29], v[156:159], v[228:231], v[26:29]
	v_mfma_f32_16x16x32_bf16 v[14:17], v[144:147], v[236:239], v[14:17]
	v_mfma_f32_16x16x32_bf16 v[10:13], v[156:159], v[236:239], v[10:13]
	s_setprio 0
	s_setprio 1
	v_mfma_f32_16x16x32_bf16 v[54:57], v[176:179], v[192:195], v[54:57]
	v_mfma_f32_16x16x32_bf16 v[50:53], v[184:187], v[192:195], v[50:53]
	v_mfma_f32_16x16x32_bf16 v[38:41], v[176:179], v[200:203], v[38:41]
	v_mfma_f32_16x16x32_bf16 v[34:37], v[184:187], v[200:203], v[34:37]
	v_mfma_f32_16x16x32_bf16 v[22:25], v[176:179], v[224:227], v[22:25]
	v_mfma_f32_16x16x32_bf16 v[18:21], v[184:187], v[224:227], v[18:21]
	v_mfma_f32_16x16x32_bf16 v[6:9], v[176:179], v[232:235], v[6:9]
	v_mfma_f32_16x16x32_bf16 v[2:5], v[184:187], v[232:235], v[2:5]
	v_mfma_f32_16x16x32_bf16 v[54:57], v[180:183], v[196:199], v[54:57]
	v_mfma_f32_16x16x32_bf16 v[50:53], v[188:191], v[196:199], v[50:53]
	v_mfma_f32_16x16x32_bf16 v[38:41], v[180:183], v[204:207], v[38:41]
	v_mfma_f32_16x16x32_bf16 v[34:37], v[188:191], v[204:207], v[34:37]
	v_mfma_f32_16x16x32_bf16 v[22:25], v[180:183], v[228:231], v[22:25]
	v_mfma_f32_16x16x32_bf16 v[18:21], v[188:191], v[228:231], v[18:21]
	v_mfma_f32_16x16x32_bf16 v[6:9], v[180:183], v[236:239], v[6:9]
	v_mfma_f32_16x16x32_bf16 v[2:5], v[188:191], v[236:239], v[2:5]
	s_setprio 0
	s_barrier
	s_andn2_b64 vcc, exec, s[12:13]
	s_mov_b64 s[14:15], -1
	s_mov_b64 s[12:13], 0
	s_mov_b64 s[24:25], 0x100
	s_cbranch_vccz .LBB0_933
	s_lshl_b32 s7, s16, 8
	s_add_i32 s7, s7, s50
	v_or_b32_e32 v140, s7, v152
	v_or_b32_e32 v148, 16, v140
	v_or_b32_e32 v146, 32, v140
	v_or_b32_e32 v144, 48, v140
	s_mov_b64 s[12:13], -1
	s_cmp_gt_i32 s55, 3
	v_ashrrev_i32_e32 v141, 31, v140
	v_ashrrev_i32_e32 v149, 31, v148
	v_ashrrev_i32_e32 v147, 31, v146
	v_ashrrev_i32_e32 v145, 31, v144
	v_add_u32_e32 v142, 0x80, v140
	s_cbranch_scc0 .LBB0_936
	v_lshlrev_b64 v[150:151], 6, v[140:141]
	v_lshl_add_u64 v[150:151], s[0:1], 0, v[150:151]
	v_add_co_u32_e32 v150, vcc, 0x20864000, v150
	s_lshl_b32 s5, s55, 1
	s_nop 0
	v_addc_co_u32_e32 v151, vcc, 0, v151, vcc
	global_load_dwordx4 v[180:183], v[150:151], off offset:288
	global_load_dwordx4 v[184:187], v[150:151], off offset:1312
	global_load_dwordx4 v[188:191], v[150:151], off offset:2336
	global_load_dwordx4 v[192:195], v[150:151], off offset:3360
	v_add_co_u32_e32 v228, vcc, 0x2000, v150
	s_nop 1
	v_addc_co_u32_e32 v229, vcc, 0, v151, vcc
	global_load_dwordx4 v[196:199], v[228:229], off offset:288
	global_load_dwordx4 v[200:203], v[228:229], off offset:1312
	global_load_dwordx4 v[204:207], v[228:229], off offset:2336
	global_load_dwordx4 v[224:227], v[228:229], off offset:3360
	s_lshr_b32 s7, s7, 8
	s_addk_i32 s5, 0x3ff8
	s_and_b32 s7, s7, 0x3ff8
	s_add_i32 s7, s7, s5
	s_movk_i32 s14, 0x7cf
	s_lshl_b32 s12, s7, 18
	s_or_b32 s7, s12, 0x40000
	s_mov_b32 s18, 0x20864000
	s_movk_i32 s15, 0x7df
	s_movk_i32 s16, 0x7ef
	s_movk_i32 s13, 0x7ff
	s_waitcnt vmcnt(0) lgkmcnt(0)
; __device__ __forceinline__ bf16_t f2bf(float x) { return (bf16_t)(pk2(x, 0.f) & 0xffffu); }
;     __device__ __forceinline__ void operator()(AccRef acc, const pg8::Unit& u, int wr, int wc, int fr, int fq) const {
;     ...
;         } else if (WHICH == 1) {
;             bf16_t* VT = (bf16_t*)(ws + WS_VAT); const int h0 = (pn - 4) * 2;
; #pragma unroll
;             for (int ai = 0; ai < 2; ++ai)
; #pragma unroll
;                 for (int m = 0; m < 4; ++m) { const int row = row0 + ai * 128 + m * 16; const int b = row >> 11, s = row & 2047; const float rs = rstd(row);
; #pragma unroll
;                     for (int bj = 0; bj < 2; ++bj) { const unsigned po = (unsigned)(((b * 8 + h0 + bj) * 128 + cl0) * 2048 + s);
; #pragma unroll
;                         for (int n = 0; n < 2; ++n)
; #pragma unroll
;                             for (int j = 0; j < 4; ++j) VT[po + (unsigned)((4 * n + j) * 2048)] = f2bf(acc[ai][bj][m][n][j] * rs); }
;                     asm volatile("" ::: "memory"); }
	v_mov_b64_e32 v[156:157], v[180:181]
	v_mov_b64_e32 v[158:159], v[182:183]
	v_mov_b32_e32 v150, v157
	v_mov_b32_e32 v151, v158
	v_mov_b32_e32 v157, v159
	v_pk_add_f32 v[150:151], v[150:151], v[156:157]
	v_and_or_b32 v156, v140, s14, v154
	v_add_f32_e32 v0, v150, v151
	v_fmamk_f32 v0, v0, 0x3b800000, v220
	v_cmp_gt_f32_e32 vcc, s69, v0
	v_mul_f32_e32 v143, 0x4b800000, v0
	s_nop 0
	v_cndmask_b32_e32 v0, v0, v143, vcc
	v_rsq_f32_e32 v0, v0
	s_nop 0
	v_mul_f32_e32 v143, 0x45800000, v0
	v_cndmask_b32_e32 v143, v0, v143, vcc
	v_or_b32_e32 v0, s12, v156
	v_mul_f32_e32 v150, v126, v143
	v_cvt_pk_bf16_f32 v157, v150, s0
	v_lshl_add_u64 v[150:151], v[0:1], 1, s[2:3]
	flat_store_short v[150:151], v157
	v_mul_f32_e32 v150, v127, v143
	v_cvt_pk_bf16_f32 v157, v150, s0
	v_or_b32_e32 v150, 0x800, v0
	v_mov_b32_e32 v151, v1
	v_lshl_add_u64 v[150:151], v[150:151], 1, s[2:3]
	flat_store_short v[150:151], v157
	v_mul_f32_e32 v150, v128, v143
	v_cvt_pk_bf16_f32 v157, v150, s0
	v_or_b32_e32 v150, 0x1000, v0
	v_mov_b32_e32 v151, v1
	v_lshl_add_u64 v[150:151], v[150:151], 1, s[2:3]
	flat_store_short v[150:151], v157
	v_mul_f32_e32 v150, v129, v143
	v_cvt_pk_bf16_f32 v157, v150, s0
	v_or_b32_e32 v150, 0x1800, v0
	v_mov_b32_e32 v151, v1
	v_lshl_add_u64 v[150:151], v[150:151], 1, s[2:3]
	flat_store_short v[150:151], v157
	v_mul_f32_e32 v151, v122, v143
	v_or_b32_e32 v150, 0x2000, v0
	v_cvt_pk_bf16_f32 v157, v151, s0
	v_mov_b32_e32 v151, v1
	v_lshl_add_u64 v[150:151], v[150:151], 1, s[2:3]
	flat_store_short v[150:151], v157
	v_mul_f32_e32 v150, v123, v143
	v_cvt_pk_bf16_f32 v157, v150, s0
	v_or_b32_e32 v150, 0x2800, v0
	v_mov_b32_e32 v151, v1
	v_lshl_add_u64 v[150:151], v[150:151], 1, s[2:3]
	flat_store_short v[150:151], v157
	v_mul_f32_e32 v150, v124, v143
	v_cvt_pk_bf16_f32 v157, v150, s0
	v_or_b32_e32 v150, 0x3000, v0
	v_mov_b32_e32 v151, v1
	v_lshl_add_u64 v[150:151], v[150:151], 1, s[2:3]
	flat_store_short v[150:151], v157
	v_mul_f32_e32 v150, v125, v143
	v_or_b32_e32 v0, 0x3800, v0
	v_cvt_pk_bf16_f32 v157, v150, s0
	v_lshl_add_u64 v[150:151], v[0:1], 1, s[2:3]
	flat_store_short v[150:151], v157
	v_or_b32_e32 v0, s7, v156
	v_mul_f32_e32 v150, v118, v143
	v_cvt_pk_bf16_f32 v156, v150, s0
	v_lshl_add_u64 v[150:151], v[0:1], 1, s[2:3]
	flat_store_short v[150:151], v156
	v_mul_f32_e32 v150, v119, v143
	v_cvt_pk_bf16_f32 v156, v150, s0
	v_or_b32_e32 v150, 0x800, v0
	v_mov_b32_e32 v151, v1
	v_lshl_add_u64 v[150:151], v[150:151], 1, s[2:3]
	flat_store_short v[150:151], v156
	v_mul_f32_e32 v150, v120, v143
	v_cvt_pk_bf16_f32 v156, v150, s0
	v_or_b32_e32 v150, 0x1000, v0
	v_mov_b32_e32 v151, v1
	v_lshl_add_u64 v[150:151], v[150:151], 1, s[2:3]
	flat_store_short v[150:151], v156
	v_mul_f32_e32 v150, v121, v143
	v_cvt_pk_bf16_f32 v156, v150, s0
	v_or_b32_e32 v150, 0x1800, v0
	v_mov_b32_e32 v151, v1
	v_lshl_add_u64 v[150:151], v[150:151], 1, s[2:3]
	flat_store_short v[150:151], v156
	v_mul_f32_e32 v151, v114, v143
	v_or_b32_e32 v150, 0x2000, v0
	v_cvt_pk_bf16_f32 v156, v151, s0
	v_mov_b32_e32 v151, v1
	v_lshl_add_u64 v[150:151], v[150:151], 1, s[2:3]
	flat_store_short v[150:151], v156
	v_mul_f32_e32 v150, v115, v143
	v_cvt_pk_bf16_f32 v156, v150, s0
	v_or_b32_e32 v150, 0x2800, v0
	v_mov_b32_e32 v151, v1
	v_lshl_add_u64 v[150:151], v[150:151], 1, s[2:3]
	flat_store_short v[150:151], v156
	v_mul_f32_e32 v150, v116, v143
	v_cvt_pk_bf16_f32 v156, v150, s0
	v_or_b32_e32 v150, 0x3000, v0
	v_mov_b32_e32 v151, v1
	v_lshl_add_u64 v[150:151], v[150:151], 1, s[2:3]
	v_mul_f32_e32 v143, v117, v143
	v_or_b32_e32 v0, 0x3800, v0
	flat_store_short v[150:151], v156
	v_cvt_pk_bf16_f32 v143, v143, s0
	v_lshl_add_u64 v[150:151], v[0:1], 1, s[2:3]
	flat_store_short v[150:151], v143
	v_lshlrev_b64 v[150:151], 6, v[148:149]
	v_lshl_add_u64 v[150:151], s[0:1], 0, v[150:151]
	v_add_co_u32_e32 v150, vcc, s18, v150
	s_nop 1
	v_addc_co_u32_e32 v151, vcc, 0, v151, vcc
	v_mov_b64_e32 v[156:157], v[184:185]
	v_mov_b64_e32 v[158:159], v[186:187]
	v_mov_b32_e32 v150, v157
	v_mov_b32_e32 v151, v158
	v_mov_b32_e32 v157, v159
	v_pk_add_f32 v[150:151], v[150:151], v[156:157]
	v_and_or_b32 v156, v148, s15, v154
	v_add_f32_e32 v0, v150, v151
	v_fmamk_f32 v0, v0, 0x3b800000, v220
	v_cmp_gt_f32_e32 vcc, s69, v0
	v_mul_f32_e32 v143, 0x4b800000, v0
	s_nop 0
	v_cndmask_b32_e32 v0, v0, v143, vcc
	v_rsq_f32_e32 v0, v0
	s_nop 0
	v_mul_f32_e32 v143, 0x45800000, v0
	v_cndmask_b32_e32 v143, v0, v143, vcc
	v_or_b32_e32 v0, s12, v156
	v_mul_f32_e32 v150, v110, v143
	v_cvt_pk_bf16_f32 v157, v150, s0
	v_lshl_add_u64 v[150:151], v[0:1], 1, s[2:3]
	flat_store_short v[150:151], v157
	v_mul_f32_e32 v150, v111, v143
	v_cvt_pk_bf16_f32 v157, v150, s0
	v_or_b32_e32 v150, 0x800, v0
	v_mov_b32_e32 v151, v1
	v_lshl_add_u64 v[150:151], v[150:151], 1, s[2:3]
	flat_store_short v[150:151], v157
	v_mul_f32_e32 v150, v112, v143
	v_cvt_pk_bf16_f32 v157, v150, s0
	v_or_b32_e32 v150, 0x1000, v0
	v_mov_b32_e32 v151, v1
	v_lshl_add_u64 v[150:151], v[150:151], 1, s[2:3]
	flat_store_short v[150:151], v157
	v_mul_f32_e32 v150, v113, v143
	v_cvt_pk_bf16_f32 v157, v150, s0
	v_or_b32_e32 v150, 0x1800, v0
	v_mov_b32_e32 v151, v1
	v_lshl_add_u64 v[150:151], v[150:151], 1, s[2:3]
	flat_store_short v[150:151], v157
	v_mul_f32_e32 v151, v106, v143
	v_or_b32_e32 v150, 0x2000, v0
	v_cvt_pk_bf16_f32 v157, v151, s0
	v_mov_b32_e32 v151, v1
	v_lshl_add_u64 v[150:151], v[150:151], 1, s[2:3]
	flat_store_short v[150:151], v157
	v_mul_f32_e32 v150, v107, v143
	v_cvt_pk_bf16_f32 v157, v150, s0
	v_or_b32_e32 v150, 0x2800, v0
	v_mov_b32_e32 v151, v1
	v_lshl_add_u64 v[150:151], v[150:151], 1, s[2:3]
	flat_store_short v[150:151], v157
	v_mul_f32_e32 v150, v108, v143
; __device__ __forceinline__ bf16_t f2bf(float x) { return (bf16_t)(pk2(x, 0.f) & 0xffffu); }
;     __device__ __forceinline__ void operator()(AccRef acc, const pg8::Unit& u, int wr, int wc, int fr, int fq) const {
;     ...
;         } else if (WHICH == 1) {
;             bf16_t* VT = (bf16_t*)(ws + WS_VAT); const int h0 = (pn - 4) * 2;
; #pragma unroll
;             for (int ai = 0; ai < 2; ++ai)
; #pragma unroll
;                 for (int m = 0; m < 4; ++m) { const int row = row0 + ai * 128 + m * 16; const int b = row >> 11, s = row & 2047; const float rs = rstd(row);
; #pragma unroll
;                     for (int bj = 0; bj < 2; ++bj) { const unsigned po = (unsigned)(((b * 8 + h0 + bj) * 128 + cl0) * 2048 + s);
; #pragma unroll
;                         for (int n = 0; n < 2; ++n)
; #pragma unroll
;                             for (int j = 0; j < 4; ++j) VT[po + (unsigned)((4 * n + j) * 2048)] = f2bf(acc[ai][bj][m][n][j] * rs); }
;                     asm volatile("" ::: "memory"); }
	v_cvt_pk_bf16_f32 v157, v150, s0
	v_or_b32_e32 v150, 0x3000, v0
	v_mov_b32_e32 v151, v1
	v_lshl_add_u64 v[150:151], v[150:151], 1, s[2:3]
	flat_store_short v[150:151], v157
	v_mul_f32_e32 v150, v109, v143
	v_or_b32_e32 v0, 0x3800, v0
	v_cvt_pk_bf16_f32 v157, v150, s0
	v_lshl_add_u64 v[150:151], v[0:1], 1, s[2:3]
	flat_store_short v[150:151], v157
	v_or_b32_e32 v0, s7, v156
	v_mul_f32_e32 v150, v102, v143
	v_cvt_pk_bf16_f32 v156, v150, s0
	v_lshl_add_u64 v[150:151], v[0:1], 1, s[2:3]
	flat_store_short v[150:151], v156
	v_mul_f32_e32 v150, v103, v143
	v_cvt_pk_bf16_f32 v156, v150, s0
	v_or_b32_e32 v150, 0x800, v0
	v_mov_b32_e32 v151, v1
	v_lshl_add_u64 v[150:151], v[150:151], 1, s[2:3]
	flat_store_short v[150:151], v156
	v_mul_f32_e32 v150, v104, v143
	v_cvt_pk_bf16_f32 v156, v150, s0
	v_or_b32_e32 v150, 0x1000, v0
	v_mov_b32_e32 v151, v1
	v_lshl_add_u64 v[150:151], v[150:151], 1, s[2:3]
	flat_store_short v[150:151], v156
	v_mul_f32_e32 v150, v105, v143
	v_cvt_pk_bf16_f32 v156, v150, s0
	v_or_b32_e32 v150, 0x1800, v0
	v_mov_b32_e32 v151, v1
	v_lshl_add_u64 v[150:151], v[150:151], 1, s[2:3]
	flat_store_short v[150:151], v156
	v_mul_f32_e32 v151, v98, v143
	v_or_b32_e32 v150, 0x2000, v0
	v_cvt_pk_bf16_f32 v156, v151, s0
	v_mov_b32_e32 v151, v1
	v_lshl_add_u64 v[150:151], v[150:151], 1, s[2:3]
	flat_store_short v[150:151], v156
	v_mul_f32_e32 v150, v99, v143
	v_cvt_pk_bf16_f32 v156, v150, s0
	v_or_b32_e32 v150, 0x2800, v0
	v_mov_b32_e32 v151, v1
	v_lshl_add_u64 v[150:151], v[150:151], 1, s[2:3]
	flat_store_short v[150:151], v156
	v_mul_f32_e32 v150, v100, v143
	v_cvt_pk_bf16_f32 v156, v150, s0
	v_or_b32_e32 v150, 0x3000, v0
	v_mov_b32_e32 v151, v1
	v_lshl_add_u64 v[150:151], v[150:151], 1, s[2:3]
	v_mul_f32_e32 v143, v101, v143
	v_or_b32_e32 v0, 0x3800, v0
	flat_store_short v[150:151], v156
	v_cvt_pk_bf16_f32 v143, v143, s0
	v_lshl_add_u64 v[150:151], v[0:1], 1, s[2:3]
	flat_store_short v[150:151], v143
	v_lshlrev_b64 v[150:151], 6, v[146:147]
	v_lshl_add_u64 v[150:151], s[0:1], 0, v[150:151]
	v_add_co_u32_e32 v150, vcc, s18, v150
	s_nop 1
	v_addc_co_u32_e32 v151, vcc, 0, v151, vcc
	v_mov_b64_e32 v[156:157], v[188:189]
	v_mov_b64_e32 v[158:159], v[190:191]
	v_mov_b32_e32 v150, v157
	v_mov_b32_e32 v151, v158
	v_mov_b32_e32 v157, v159
	v_pk_add_f32 v[150:151], v[150:151], v[156:157]
	v_and_or_b32 v156, v146, s16, v154
	v_add_f32_e32 v0, v150, v151
	v_fmamk_f32 v0, v0, 0x3b800000, v220
	v_cmp_gt_f32_e32 vcc, s69, v0
	v_mul_f32_e32 v143, 0x4b800000, v0
	s_nop 0
	v_cndmask_b32_e32 v0, v0, v143, vcc
	v_rsq_f32_e32 v0, v0
	s_nop 0
	v_mul_f32_e32 v143, 0x45800000, v0
	v_cndmask_b32_e32 v143, v0, v143, vcc
	v_or_b32_e32 v0, s12, v156
	v_mul_f32_e32 v150, v94, v143
	v_cvt_pk_bf16_f32 v157, v150, s0
	v_lshl_add_u64 v[150:151], v[0:1], 1, s[2:3]
	flat_store_short v[150:151], v157
	v_mul_f32_e32 v150, v95, v143
	v_cvt_pk_bf16_f32 v157, v150, s0
	v_or_b32_e32 v150, 0x800, v0
	v_mov_b32_e32 v151, v1
	v_lshl_add_u64 v[150:151], v[150:151], 1, s[2:3]
	flat_store_short v[150:151], v157
	v_mul_f32_e32 v150, v96, v143
	v_cvt_pk_bf16_f32 v157, v150, s0
	v_or_b32_e32 v150, 0x1000, v0
	v_mov_b32_e32 v151, v1
	v_lshl_add_u64 v[150:151], v[150:151], 1, s[2:3]
	flat_store_short v[150:151], v157
	v_mul_f32_e32 v150, v97, v143
	v_cvt_pk_bf16_f32 v157, v150, s0
	v_or_b32_e32 v150, 0x1800, v0
	v_mov_b32_e32 v151, v1
	v_lshl_add_u64 v[150:151], v[150:151], 1, s[2:3]
	flat_store_short v[150:151], v157
	v_mul_f32_e32 v151, v90, v143
	v_or_b32_e32 v150, 0x2000, v0
	v_cvt_pk_bf16_f32 v157, v151, s0
	v_mov_b32_e32 v151, v1
	v_lshl_add_u64 v[150:151], v[150:151], 1, s[2:3]
	flat_store_short v[150:151], v157
	v_mul_f32_e32 v150, v91, v143
	v_cvt_pk_bf16_f32 v157, v150, s0
	v_or_b32_e32 v150, 0x2800, v0
	v_mov_b32_e32 v151, v1
	v_lshl_add_u64 v[150:151], v[150:151], 1, s[2:3]
	flat_store_short v[150:151], v157
	v_mul_f32_e32 v150, v92, v143
	v_cvt_pk_bf16_f32 v157, v150, s0
	v_or_b32_e32 v150, 0x3000, v0
	v_mov_b32_e32 v151, v1
	v_lshl_add_u64 v[150:151], v[150:151], 1, s[2:3]
	flat_store_short v[150:151], v157
	v_mul_f32_e32 v150, v93, v143
	v_or_b32_e32 v0, 0x3800, v0
	v_cvt_pk_bf16_f32 v157, v150, s0
	v_lshl_add_u64 v[150:151], v[0:1], 1, s[2:3]
	flat_store_short v[150:151], v157
	v_or_b32_e32 v0, s7, v156
	v_mul_f32_e32 v150, v86, v143
	v_cvt_pk_bf16_f32 v156, v150, s0
	v_lshl_add_u64 v[150:151], v[0:1], 1, s[2:3]
	flat_store_short v[150:151], v156
	v_mul_f32_e32 v150, v87, v143
	v_cvt_pk_bf16_f32 v156, v150, s0
	v_or_b32_e32 v150, 0x800, v0
	v_mov_b32_e32 v151, v1
	v_lshl_add_u64 v[150:151], v[150:151], 1, s[2:3]
	flat_store_short v[150:151], v156
	v_mul_f32_e32 v150, v88, v143
	v_cvt_pk_bf16_f32 v156, v150, s0
	v_or_b32_e32 v150, 0x1000, v0
	v_mov_b32_e32 v151, v1
	v_lshl_add_u64 v[150:151], v[150:151], 1, s[2:3]
	flat_store_short v[150:151], v156
	v_mul_f32_e32 v150, v89, v143
	v_cvt_pk_bf16_f32 v156, v150, s0
	v_or_b32_e32 v150, 0x1800, v0
	v_mov_b32_e32 v151, v1
	v_lshl_add_u64 v[150:151], v[150:151], 1, s[2:3]
	flat_store_short v[150:151], v156
	v_mul_f32_e32 v151, v82, v143
	v_or_b32_e32 v150, 0x2000, v0
	v_cvt_pk_bf16_f32 v156, v151, s0
	v_mov_b32_e32 v151, v1
	v_lshl_add_u64 v[150:151], v[150:151], 1, s[2:3]
	flat_store_short v[150:151], v156
	v_mul_f32_e32 v150, v83, v143
	v_cvt_pk_bf16_f32 v156, v150, s0
	v_or_b32_e32 v150, 0x2800, v0
	v_mov_b32_e32 v151, v1
	v_lshl_add_u64 v[150:151], v[150:151], 1, s[2:3]
	flat_store_short v[150:151], v156
	v_mul_f32_e32 v150, v84, v143
	v_cvt_pk_bf16_f32 v156, v150, s0
	v_or_b32_e32 v150, 0x3000, v0
	v_mov_b32_e32 v151, v1
	v_lshl_add_u64 v[150:151], v[150:151], 1, s[2:3]
	v_mul_f32_e32 v143, v85, v143
	v_or_b32_e32 v0, 0x3800, v0
; __device__ __forceinline__ bf16_t f2bf(float x) { return (bf16_t)(pk2(x, 0.f) & 0xffffu); }
;     __device__ __forceinline__ void operator()(AccRef acc, const pg8::Unit& u, int wr, int wc, int fr, int fq) const {
;     ...
;         } else if (WHICH == 1) {
;             bf16_t* VT = (bf16_t*)(ws + WS_VAT); const int h0 = (pn - 4) * 2;
; #pragma unroll
;             for (int ai = 0; ai < 2; ++ai)
; #pragma unroll
;                 for (int m = 0; m < 4; ++m) { const int row = row0 + ai * 128 + m * 16; const int b = row >> 11, s = row & 2047; const float rs = rstd(row);
; #pragma unroll
;                     for (int bj = 0; bj < 2; ++bj) { const unsigned po = (unsigned)(((b * 8 + h0 + bj) * 128 + cl0) * 2048 + s);
; #pragma unroll
;                         for (int n = 0; n < 2; ++n)
; #pragma unroll
;                             for (int j = 0; j < 4; ++j) VT[po + (unsigned)((4 * n + j) * 2048)] = f2bf(acc[ai][bj][m][n][j] * rs); }
;                     asm volatile("" ::: "memory"); }
	flat_store_short v[150:151], v156
	v_cvt_pk_bf16_f32 v143, v143, s0
	v_lshl_add_u64 v[150:151], v[0:1], 1, s[2:3]
	flat_store_short v[150:151], v143
	v_lshlrev_b64 v[150:151], 6, v[144:145]
	v_lshl_add_u64 v[150:151], s[0:1], 0, v[150:151]
	v_add_co_u32_e32 v150, vcc, s18, v150
	s_nop 1
	v_addc_co_u32_e32 v151, vcc, 0, v151, vcc
	v_mov_b64_e32 v[156:157], v[192:193]
	v_mov_b64_e32 v[158:159], v[194:195]
	v_mov_b32_e32 v150, v157
	v_mov_b32_e32 v151, v158
	v_mov_b32_e32 v157, v159
	v_pk_add_f32 v[150:151], v[150:151], v[156:157]
	v_and_or_b32 v156, v144, s13, v154
	v_add_f32_e32 v0, v150, v151
	v_fmamk_f32 v0, v0, 0x3b800000, v220
	v_cmp_gt_f32_e32 vcc, s69, v0
	v_mul_f32_e32 v143, 0x4b800000, v0
	s_nop 0
	v_cndmask_b32_e32 v0, v0, v143, vcc
	v_rsq_f32_e32 v0, v0
	s_nop 0
	v_mul_f32_e32 v143, 0x45800000, v0
	v_cndmask_b32_e32 v143, v0, v143, vcc
	v_or_b32_e32 v0, s12, v156
	v_mul_f32_e32 v150, v78, v143
	v_cvt_pk_bf16_f32 v157, v150, s0
	v_lshl_add_u64 v[150:151], v[0:1], 1, s[2:3]
	flat_store_short v[150:151], v157
	v_mul_f32_e32 v150, v79, v143
	v_cvt_pk_bf16_f32 v157, v150, s0
	v_or_b32_e32 v150, 0x800, v0
	v_mov_b32_e32 v151, v1
	v_lshl_add_u64 v[150:151], v[150:151], 1, s[2:3]
	flat_store_short v[150:151], v157
	v_mul_f32_e32 v150, v80, v143
	v_cvt_pk_bf16_f32 v157, v150, s0
	v_or_b32_e32 v150, 0x1000, v0
	v_mov_b32_e32 v151, v1
	v_lshl_add_u64 v[150:151], v[150:151], 1, s[2:3]
	flat_store_short v[150:151], v157
	v_mul_f32_e32 v150, v81, v143
	v_cvt_pk_bf16_f32 v157, v150, s0
	v_or_b32_e32 v150, 0x1800, v0
	v_mov_b32_e32 v151, v1
	v_lshl_add_u64 v[150:151], v[150:151], 1, s[2:3]
	flat_store_short v[150:151], v157
	v_mul_f32_e32 v151, v74, v143
	v_or_b32_e32 v150, 0x2000, v0
	v_cvt_pk_bf16_f32 v157, v151, s0
	v_mov_b32_e32 v151, v1
	v_lshl_add_u64 v[150:151], v[150:151], 1, s[2:3]
	flat_store_short v[150:151], v157
	v_mul_f32_e32 v150, v75, v143
	v_cvt_pk_bf16_f32 v157, v150, s0
	v_or_b32_e32 v150, 0x2800, v0
	v_mov_b32_e32 v151, v1
	v_lshl_add_u64 v[150:151], v[150:151], 1, s[2:3]
	flat_store_short v[150:151], v157
	v_mul_f32_e32 v150, v76, v143
	v_cvt_pk_bf16_f32 v157, v150, s0
	v_or_b32_e32 v150, 0x3000, v0
	v_mov_b32_e32 v151, v1
	v_lshl_add_u64 v[150:151], v[150:151], 1, s[2:3]
	flat_store_short v[150:151], v157
	v_mul_f32_e32 v150, v77, v143
	v_or_b32_e32 v0, 0x3800, v0
	v_cvt_pk_bf16_f32 v157, v150, s0
	v_lshl_add_u64 v[150:151], v[0:1], 1, s[2:3]
	flat_store_short v[150:151], v157
	v_or_b32_e32 v0, s7, v156
	v_mul_f32_e32 v150, v70, v143
	v_cvt_pk_bf16_f32 v156, v150, s0
	v_lshl_add_u64 v[150:151], v[0:1], 1, s[2:3]
	flat_store_short v[150:151], v156
	v_mul_f32_e32 v150, v71, v143
	v_cvt_pk_bf16_f32 v156, v150, s0
	v_or_b32_e32 v150, 0x800, v0
	v_mov_b32_e32 v151, v1
	v_lshl_add_u64 v[150:151], v[150:151], 1, s[2:3]
	flat_store_short v[150:151], v156
	v_mul_f32_e32 v150, v72, v143
	v_cvt_pk_bf16_f32 v156, v150, s0
	v_or_b32_e32 v150, 0x1000, v0
	v_mov_b32_e32 v151, v1
	v_lshl_add_u64 v[150:151], v[150:151], 1, s[2:3]
	flat_store_short v[150:151], v156
	v_mul_f32_e32 v150, v73, v143
	v_cvt_pk_bf16_f32 v156, v150, s0
	v_or_b32_e32 v150, 0x1800, v0
	v_mov_b32_e32 v151, v1
	v_lshl_add_u64 v[150:151], v[150:151], 1, s[2:3]
	flat_store_short v[150:151], v156
	v_mul_f32_e32 v151, v66, v143
	v_or_b32_e32 v150, 0x2000, v0
	v_cvt_pk_bf16_f32 v156, v151, s0
	v_mov_b32_e32 v151, v1
	v_lshl_add_u64 v[150:151], v[150:151], 1, s[2:3]
	flat_store_short v[150:151], v156
	v_mul_f32_e32 v150, v67, v143
	v_cvt_pk_bf16_f32 v156, v150, s0
	v_or_b32_e32 v150, 0x2800, v0
	v_mov_b32_e32 v151, v1
	v_lshl_add_u64 v[150:151], v[150:151], 1, s[2:3]
	flat_store_short v[150:151], v156
	v_mul_f32_e32 v150, v68, v143
	v_cvt_pk_bf16_f32 v156, v150, s0
	v_or_b32_e32 v150, 0x3000, v0
	v_mov_b32_e32 v151, v1
	v_lshl_add_u64 v[150:151], v[150:151], 1, s[2:3]
	v_mul_f32_e32 v143, v69, v143
	v_or_b32_e32 v0, 0x3800, v0
	flat_store_short v[150:151], v156
	v_cvt_pk_bf16_f32 v143, v143, s0
	v_lshl_add_u64 v[150:151], v[0:1], 1, s[2:3]
	flat_store_short v[150:151], v143
	v_ashrrev_i32_e32 v143, 31, v142
	v_lshlrev_b64 v[150:151], 6, v[142:143]
	v_lshl_add_u64 v[150:151], s[0:1], 0, v[150:151]
	v_add_co_u32_e32 v150, vcc, s18, v150
	v_lshrrev_b32_e32 v0, 8, v142
	s_nop 0
	v_addc_co_u32_e32 v151, vcc, 0, v151, vcc
	v_and_b32_e32 v0, 0x3ff8, v0
	v_add_lshl_u32 v167, v0, s5, 18
	v_or_b32_e32 v176, 0x40000, v167
	v_mov_b64_e32 v[156:157], v[196:197]
	v_mov_b64_e32 v[158:159], v[198:199]
	v_mov_b32_e32 v150, v157
	v_mov_b32_e32 v151, v158
	v_mov_b32_e32 v157, v159
	v_pk_add_f32 v[150:151], v[150:151], v[156:157]
	v_and_or_b32 v156, v142, s14, v154
	v_add_f32_e32 v143, v150, v151
	v_fmamk_f32 v143, v143, 0x3b800000, v220
	v_cmp_gt_f32_e32 vcc, s69, v143
	v_mul_f32_e32 v150, 0x4b800000, v143
	v_or_b32_e32 v0, v167, v156
	v_cndmask_b32_e32 v143, v143, v150, vcc
	v_rsq_f32_e32 v143, v143
	s_nop 0
	v_mul_f32_e32 v150, 0x45800000, v143
	v_cndmask_b32_e32 v143, v143, v150, vcc
	v_mul_f32_e32 v150, v62, v143
	v_cvt_pk_bf16_f32 v157, v150, s0
	v_lshl_add_u64 v[150:151], v[0:1], 1, s[2:3]
	flat_store_short v[150:151], v157
	v_mul_f32_e32 v150, v63, v143
	v_cvt_pk_bf16_f32 v157, v150, s0
	v_or_b32_e32 v150, 0x800, v0
	v_mov_b32_e32 v151, v1
	v_lshl_add_u64 v[150:151], v[150:151], 1, s[2:3]
	flat_store_short v[150:151], v157
	v_mul_f32_e32 v150, v64, v143
	v_cvt_pk_bf16_f32 v157, v150, s0
	v_or_b32_e32 v150, 0x1000, v0
	v_mov_b32_e32 v151, v1
	v_lshl_add_u64 v[150:151], v[150:151], 1, s[2:3]
	flat_store_short v[150:151], v157
	v_mul_f32_e32 v150, v65, v143
	v_cvt_pk_bf16_f32 v157, v150, s0
	v_or_b32_e32 v150, 0x1800, v0
	v_mov_b32_e32 v151, v1
	v_lshl_add_u64 v[150:151], v[150:151], 1, s[2:3]
; __device__ __forceinline__ bf16_t f2bf(float x) { return (bf16_t)(pk2(x, 0.f) & 0xffffu); }
;     __device__ __forceinline__ void operator()(AccRef acc, const pg8::Unit& u, int wr, int wc, int fr, int fq) const {
;     ...
;         } else if (WHICH == 1) {
;             bf16_t* VT = (bf16_t*)(ws + WS_VAT); const int h0 = (pn - 4) * 2;
; #pragma unroll
;             for (int ai = 0; ai < 2; ++ai)
; #pragma unroll
;                 for (int m = 0; m < 4; ++m) { const int row = row0 + ai * 128 + m * 16; const int b = row >> 11, s = row & 2047; const float rs = rstd(row);
; #pragma unroll
;                     for (int bj = 0; bj < 2; ++bj) { const unsigned po = (unsigned)(((b * 8 + h0 + bj) * 128 + cl0) * 2048 + s);
; #pragma unroll
;                         for (int n = 0; n < 2; ++n)
; #pragma unroll
;                             for (int j = 0; j < 4; ++j) VT[po + (unsigned)((4 * n + j) * 2048)] = f2bf(acc[ai][bj][m][n][j] * rs); }
;                     asm volatile("" ::: "memory"); }
	flat_store_short v[150:151], v157
	v_mul_f32_e32 v151, v58, v143
	v_or_b32_e32 v150, 0x2000, v0
	v_cvt_pk_bf16_f32 v157, v151, s0
	v_mov_b32_e32 v151, v1
	v_lshl_add_u64 v[150:151], v[150:151], 1, s[2:3]
	flat_store_short v[150:151], v157
	v_mul_f32_e32 v150, v59, v143
	v_cvt_pk_bf16_f32 v157, v150, s0
	v_or_b32_e32 v150, 0x2800, v0
	v_mov_b32_e32 v151, v1
	v_lshl_add_u64 v[150:151], v[150:151], 1, s[2:3]
	flat_store_short v[150:151], v157
	v_mul_f32_e32 v150, v60, v143
	v_cvt_pk_bf16_f32 v157, v150, s0
	v_or_b32_e32 v150, 0x3000, v0
	v_mov_b32_e32 v151, v1
	v_lshl_add_u64 v[150:151], v[150:151], 1, s[2:3]
	flat_store_short v[150:151], v157
	v_mul_f32_e32 v150, v61, v143
	v_or_b32_e32 v0, 0x3800, v0
	v_cvt_pk_bf16_f32 v157, v150, s0
	v_lshl_add_u64 v[150:151], v[0:1], 1, s[2:3]
	flat_store_short v[150:151], v157
	v_or_b32_e32 v0, v176, v156
	v_mul_f32_e32 v150, v54, v143
	v_cvt_pk_bf16_f32 v156, v150, s0
	v_lshl_add_u64 v[150:151], v[0:1], 1, s[2:3]
	flat_store_short v[150:151], v156
	v_mul_f32_e32 v150, v55, v143
	v_cvt_pk_bf16_f32 v156, v150, s0
	v_or_b32_e32 v150, 0x800, v0
	v_mov_b32_e32 v151, v1
	v_lshl_add_u64 v[150:151], v[150:151], 1, s[2:3]
	flat_store_short v[150:151], v156
	v_mul_f32_e32 v150, v56, v143
	v_cvt_pk_bf16_f32 v156, v150, s0
	v_or_b32_e32 v150, 0x1000, v0
	v_mov_b32_e32 v151, v1
	v_lshl_add_u64 v[150:151], v[150:151], 1, s[2:3]
	flat_store_short v[150:151], v156
	v_mul_f32_e32 v150, v57, v143
	v_cvt_pk_bf16_f32 v156, v150, s0
	v_or_b32_e32 v150, 0x1800, v0
	v_mov_b32_e32 v151, v1
	v_lshl_add_u64 v[150:151], v[150:151], 1, s[2:3]
	flat_store_short v[150:151], v156
	v_mul_f32_e32 v151, v50, v143
	v_or_b32_e32 v150, 0x2000, v0
	v_cvt_pk_bf16_f32 v156, v151, s0
	v_mov_b32_e32 v151, v1
	v_lshl_add_u64 v[150:151], v[150:151], 1, s[2:3]
	flat_store_short v[150:151], v156
	v_mul_f32_e32 v150, v51, v143
	v_cvt_pk_bf16_f32 v156, v150, s0
	v_or_b32_e32 v150, 0x2800, v0
	v_mov_b32_e32 v151, v1
	v_lshl_add_u64 v[150:151], v[150:151], 1, s[2:3]
	flat_store_short v[150:151], v156
	v_mul_f32_e32 v150, v52, v143
	v_cvt_pk_bf16_f32 v156, v150, s0
	v_or_b32_e32 v150, 0x3000, v0
	v_mov_b32_e32 v151, v1
	v_lshl_add_u64 v[150:151], v[150:151], 1, s[2:3]
	v_mul_f32_e32 v143, v53, v143
	v_or_b32_e32 v0, 0x3800, v0
	flat_store_short v[150:151], v156
	v_cvt_pk_bf16_f32 v143, v143, s0
	v_lshl_add_u64 v[150:151], v[0:1], 1, s[2:3]
	flat_store_short v[150:151], v143
	v_add_u32_e32 v150, 0x90, v140
	v_ashrrev_i32_e32 v151, 31, v150
	v_lshlrev_b64 v[156:157], 6, v[150:151]
	v_lshl_add_u64 v[156:157], s[0:1], 0, v[156:157]
	v_add_co_u32_e32 v156, vcc, s18, v156
	s_nop 1
	v_addc_co_u32_e32 v157, vcc, 0, v157, vcc
	v_mov_b64_e32 v[156:157], v[200:201]
	v_mov_b64_e32 v[158:159], v[202:203]
	v_mov_b32_e32 v160, v157
	v_mov_b32_e32 v161, v158
	v_mov_b32_e32 v157, v159
	v_pk_add_f32 v[156:157], v[160:161], v[156:157]
	s_nop 0
	v_add_f32_e32 v0, v156, v157
	v_fmamk_f32 v0, v0, 0x3b800000, v220
	v_cmp_gt_f32_e32 vcc, s69, v0
	v_mul_f32_e32 v143, 0x4b800000, v0
	v_and_or_b32 v156, v150, s15, v154
	v_cndmask_b32_e32 v0, v0, v143, vcc
	v_rsq_f32_e32 v0, v0
	s_nop 0
	v_mul_f32_e32 v143, 0x45800000, v0
	v_cndmask_b32_e32 v143, v0, v143, vcc
	v_or_b32_e32 v0, v167, v156
	v_mul_f32_e32 v150, v46, v143
	v_cvt_pk_bf16_f32 v157, v150, s0
	v_lshl_add_u64 v[150:151], v[0:1], 1, s[2:3]
	flat_store_short v[150:151], v157
	v_mul_f32_e32 v150, v47, v143
	v_cvt_pk_bf16_f32 v157, v150, s0
	v_or_b32_e32 v150, 0x800, v0
	v_mov_b32_e32 v151, v1
	v_lshl_add_u64 v[150:151], v[150:151], 1, s[2:3]
	flat_store_short v[150:151], v157
	v_mul_f32_e32 v150, v48, v143
	v_cvt_pk_bf16_f32 v157, v150, s0
	v_or_b32_e32 v150, 0x1000, v0
	v_mov_b32_e32 v151, v1
	v_lshl_add_u64 v[150:151], v[150:151], 1, s[2:3]
	flat_store_short v[150:151], v157
	v_mul_f32_e32 v150, v49, v143
	v_cvt_pk_bf16_f32 v157, v150, s0
	v_or_b32_e32 v150, 0x1800, v0
	v_mov_b32_e32 v151, v1
	v_lshl_add_u64 v[150:151], v[150:151], 1, s[2:3]
	flat_store_short v[150:151], v157
	v_mul_f32_e32 v151, v42, v143
	v_or_b32_e32 v150, 0x2000, v0
	v_cvt_pk_bf16_f32 v157, v151, s0
	v_mov_b32_e32 v151, v1
	v_lshl_add_u64 v[150:151], v[150:151], 1, s[2:3]
	flat_store_short v[150:151], v157
	v_mul_f32_e32 v150, v43, v143
	v_cvt_pk_bf16_f32 v157, v150, s0
	v_or_b32_e32 v150, 0x2800, v0
	v_mov_b32_e32 v151, v1
	v_lshl_add_u64 v[150:151], v[150:151], 1, s[2:3]
	flat_store_short v[150:151], v157
	v_mul_f32_e32 v150, v44, v143
	v_cvt_pk_bf16_f32 v157, v150, s0
	v_or_b32_e32 v150, 0x3000, v0
	v_mov_b32_e32 v151, v1
	v_lshl_add_u64 v[150:151], v[150:151], 1, s[2:3]
	flat_store_short v[150:151], v157
	v_mul_f32_e32 v150, v45, v143
	v_or_b32_e32 v0, 0x3800, v0
	v_cvt_pk_bf16_f32 v157, v150, s0
	v_lshl_add_u64 v[150:151], v[0:1], 1, s[2:3]
	flat_store_short v[150:151], v157
	v_or_b32_e32 v0, v176, v156
	v_mul_f32_e32 v150, v38, v143
	v_cvt_pk_bf16_f32 v156, v150, s0
	v_lshl_add_u64 v[150:151], v[0:1], 1, s[2:3]
	flat_store_short v[150:151], v156
	v_mul_f32_e32 v150, v39, v143
	v_cvt_pk_bf16_f32 v156, v150, s0
	v_or_b32_e32 v150, 0x800, v0
	v_mov_b32_e32 v151, v1
	v_lshl_add_u64 v[150:151], v[150:151], 1, s[2:3]
	flat_store_short v[150:151], v156
	v_mul_f32_e32 v150, v40, v143
	v_cvt_pk_bf16_f32 v156, v150, s0
	v_or_b32_e32 v150, 0x1000, v0
	v_mov_b32_e32 v151, v1
	v_lshl_add_u64 v[150:151], v[150:151], 1, s[2:3]
	flat_store_short v[150:151], v156
	v_mul_f32_e32 v150, v41, v143
	v_cvt_pk_bf16_f32 v156, v150, s0
	v_or_b32_e32 v150, 0x1800, v0
	v_mov_b32_e32 v151, v1
	v_lshl_add_u64 v[150:151], v[150:151], 1, s[2:3]
	flat_store_short v[150:151], v156
	v_mul_f32_e32 v151, v34, v143
	v_or_b32_e32 v150, 0x2000, v0
	v_cvt_pk_bf16_f32 v156, v151, s0
; __device__ __forceinline__ bf16_t f2bf(float x) { return (bf16_t)(pk2(x, 0.f) & 0xffffu); }
;     __device__ __forceinline__ void operator()(AccRef acc, const pg8::Unit& u, int wr, int wc, int fr, int fq) const {
;     ...
;         } else if (WHICH == 1) {
;             bf16_t* VT = (bf16_t*)(ws + WS_VAT); const int h0 = (pn - 4) * 2;
; #pragma unroll
;             for (int ai = 0; ai < 2; ++ai)
; #pragma unroll
;                 for (int m = 0; m < 4; ++m) { const int row = row0 + ai * 128 + m * 16; const int b = row >> 11, s = row & 2047; const float rs = rstd(row);
; #pragma unroll
;                     for (int bj = 0; bj < 2; ++bj) { const unsigned po = (unsigned)(((b * 8 + h0 + bj) * 128 + cl0) * 2048 + s);
; #pragma unroll
;                         for (int n = 0; n < 2; ++n)
; #pragma unroll
;                             for (int j = 0; j < 4; ++j) VT[po + (unsigned)((4 * n + j) * 2048)] = f2bf(acc[ai][bj][m][n][j] * rs); }
;                     asm volatile("" ::: "memory"); }
	v_mov_b32_e32 v151, v1
	v_lshl_add_u64 v[150:151], v[150:151], 1, s[2:3]
	flat_store_short v[150:151], v156
	v_mul_f32_e32 v150, v35, v143
	v_cvt_pk_bf16_f32 v156, v150, s0
	v_or_b32_e32 v150, 0x2800, v0
	v_mov_b32_e32 v151, v1
	v_lshl_add_u64 v[150:151], v[150:151], 1, s[2:3]
	flat_store_short v[150:151], v156
	v_mul_f32_e32 v150, v36, v143
	v_cvt_pk_bf16_f32 v156, v150, s0
	v_or_b32_e32 v150, 0x3000, v0
	v_mov_b32_e32 v151, v1
	v_lshl_add_u64 v[150:151], v[150:151], 1, s[2:3]
	v_mul_f32_e32 v143, v37, v143
	v_or_b32_e32 v0, 0x3800, v0
	flat_store_short v[150:151], v156
	v_cvt_pk_bf16_f32 v143, v143, s0
	v_lshl_add_u64 v[150:151], v[0:1], 1, s[2:3]
	flat_store_short v[150:151], v143
	v_add_u32_e32 v150, 0xa0, v140
	v_ashrrev_i32_e32 v151, 31, v150
	v_lshlrev_b64 v[156:157], 6, v[150:151]
	v_lshl_add_u64 v[156:157], s[0:1], 0, v[156:157]
	v_add_co_u32_e32 v156, vcc, s18, v156
	s_nop 1
	v_addc_co_u32_e32 v157, vcc, 0, v157, vcc
	v_mov_b64_e32 v[156:157], v[204:205]
	v_mov_b64_e32 v[158:159], v[206:207]
	v_mov_b32_e32 v160, v157
	v_mov_b32_e32 v161, v158
	v_mov_b32_e32 v157, v159
	v_pk_add_f32 v[156:157], v[160:161], v[156:157]
	s_nop 0
	v_add_f32_e32 v0, v156, v157
	v_fmamk_f32 v0, v0, 0x3b800000, v220
	v_cmp_gt_f32_e32 vcc, s69, v0
	v_mul_f32_e32 v143, 0x4b800000, v0
	v_and_or_b32 v156, v150, s16, v154
	v_cndmask_b32_e32 v0, v0, v143, vcc
	v_rsq_f32_e32 v0, v0
	s_nop 0
	v_mul_f32_e32 v143, 0x45800000, v0
	v_cndmask_b32_e32 v143, v0, v143, vcc
	v_or_b32_e32 v0, v167, v156
	v_mul_f32_e32 v150, v30, v143
	v_cvt_pk_bf16_f32 v157, v150, s0
	v_lshl_add_u64 v[150:151], v[0:1], 1, s[2:3]
	flat_store_short v[150:151], v157
	v_mul_f32_e32 v150, v31, v143
	v_cvt_pk_bf16_f32 v157, v150, s0
	v_or_b32_e32 v150, 0x800, v0
	v_mov_b32_e32 v151, v1
	v_lshl_add_u64 v[150:151], v[150:151], 1, s[2:3]
	flat_store_short v[150:151], v157
	v_mul_f32_e32 v150, v32, v143
	v_cvt_pk_bf16_f32 v157, v150, s0
	v_or_b32_e32 v150, 0x1000, v0
	v_mov_b32_e32 v151, v1
	v_lshl_add_u64 v[150:151], v[150:151], 1, s[2:3]
	flat_store_short v[150:151], v157
	v_mul_f32_e32 v150, v33, v143
	v_cvt_pk_bf16_f32 v157, v150, s0
	v_or_b32_e32 v150, 0x1800, v0
	v_mov_b32_e32 v151, v1
	v_lshl_add_u64 v[150:151], v[150:151], 1, s[2:3]
	flat_store_short v[150:151], v157
	v_mul_f32_e32 v151, v26, v143
	v_or_b32_e32 v150, 0x2000, v0
	v_cvt_pk_bf16_f32 v157, v151, s0
	v_mov_b32_e32 v151, v1
	v_lshl_add_u64 v[150:151], v[150:151], 1, s[2:3]
	flat_store_short v[150:151], v157
	v_mul_f32_e32 v150, v27, v143
	v_cvt_pk_bf16_f32 v157, v150, s0
	v_or_b32_e32 v150, 0x2800, v0
	v_mov_b32_e32 v151, v1
	v_lshl_add_u64 v[150:151], v[150:151], 1, s[2:3]
	flat_store_short v[150:151], v157
	v_mul_f32_e32 v150, v28, v143
	v_cvt_pk_bf16_f32 v157, v150, s0
	v_or_b32_e32 v150, 0x3000, v0
	v_mov_b32_e32 v151, v1
	v_lshl_add_u64 v[150:151], v[150:151], 1, s[2:3]
	flat_store_short v[150:151], v157
	v_mul_f32_e32 v150, v29, v143
	v_or_b32_e32 v0, 0x3800, v0
	v_cvt_pk_bf16_f32 v157, v150, s0
	v_lshl_add_u64 v[150:151], v[0:1], 1, s[2:3]
	flat_store_short v[150:151], v157
	v_or_b32_e32 v0, v176, v156
	v_mul_f32_e32 v150, v22, v143
	v_cvt_pk_bf16_f32 v156, v150, s0
	v_lshl_add_u64 v[150:151], v[0:1], 1, s[2:3]
	flat_store_short v[150:151], v156
	v_mul_f32_e32 v150, v23, v143
	v_cvt_pk_bf16_f32 v156, v150, s0
	v_or_b32_e32 v150, 0x800, v0
	v_mov_b32_e32 v151, v1
	v_lshl_add_u64 v[150:151], v[150:151], 1, s[2:3]
	flat_store_short v[150:151], v156
	v_mul_f32_e32 v150, v24, v143
	v_cvt_pk_bf16_f32 v156, v150, s0
	v_or_b32_e32 v150, 0x1000, v0
	v_mov_b32_e32 v151, v1
	v_lshl_add_u64 v[150:151], v[150:151], 1, s[2:3]
	flat_store_short v[150:151], v156
	v_mul_f32_e32 v150, v25, v143
	v_cvt_pk_bf16_f32 v156, v150, s0
	v_or_b32_e32 v150, 0x1800, v0
	v_mov_b32_e32 v151, v1
	v_lshl_add_u64 v[150:151], v[150:151], 1, s[2:3]
	flat_store_short v[150:151], v156
	v_mul_f32_e32 v151, v18, v143
	v_or_b32_e32 v150, 0x2000, v0
	v_cvt_pk_bf16_f32 v156, v151, s0
	v_mov_b32_e32 v151, v1
	v_lshl_add_u64 v[150:151], v[150:151], 1, s[2:3]
	flat_store_short v[150:151], v156
	v_mul_f32_e32 v150, v19, v143
	v_cvt_pk_bf16_f32 v156, v150, s0
	v_or_b32_e32 v150, 0x2800, v0
	v_mov_b32_e32 v151, v1
	v_lshl_add_u64 v[150:151], v[150:151], 1, s[2:3]
	flat_store_short v[150:151], v156
	v_mul_f32_e32 v150, v20, v143
; __device__ __forceinline__ bf16_t f2bf(float x) { return (bf16_t)(pk2(x, 0.f) & 0xffffu); }
;     __device__ __forceinline__ void operator()(AccRef acc, const pg8::Unit& u, int wr, int wc, int fr, int fq) const {
;     ...
;         } else if (WHICH == 1) {
;             bf16_t* VT = (bf16_t*)(ws + WS_VAT); const int h0 = (pn - 4) * 2;
; #pragma unroll
;             for (int ai = 0; ai < 2; ++ai)
; #pragma unroll
;                 for (int m = 0; m < 4; ++m) { const int row = row0 + ai * 128 + m * 16; const int b = row >> 11, s = row & 2047; const float rs = rstd(row);
; #pragma unroll
;                     for (int bj = 0; bj < 2; ++bj) { const unsigned po = (unsigned)(((b * 8 + h0 + bj) * 128 + cl0) * 2048 + s);
; #pragma unroll
;                         for (int n = 0; n < 2; ++n)
; #pragma unroll
;                             for (int j = 0; j < 4; ++j) VT[po + (unsigned)((4 * n + j) * 2048)] = f2bf(acc[ai][bj][m][n][j] * rs); }
;                     asm volatile("" ::: "memory"); }
	v_cvt_pk_bf16_f32 v156, v150, s0
	v_or_b32_e32 v150, 0x3000, v0
	v_mov_b32_e32 v151, v1
	v_lshl_add_u64 v[150:151], v[150:151], 1, s[2:3]
	v_mul_f32_e32 v143, v21, v143
	v_or_b32_e32 v0, 0x3800, v0
	flat_store_short v[150:151], v156
	v_cvt_pk_bf16_f32 v143, v143, s0
	v_lshl_add_u64 v[150:151], v[0:1], 1, s[2:3]
	flat_store_short v[150:151], v143
	v_add_u32_e32 v150, 0xb0, v140
	v_ashrrev_i32_e32 v151, 31, v150
	v_lshlrev_b64 v[156:157], 6, v[150:151]
	v_lshl_add_u64 v[156:157], s[0:1], 0, v[156:157]
	v_add_co_u32_e32 v156, vcc, s18, v156
	s_nop 1
	v_addc_co_u32_e32 v157, vcc, 0, v157, vcc
	v_mov_b64_e32 v[156:157], v[224:225]
	v_mov_b64_e32 v[158:159], v[226:227]
	v_mov_b32_e32 v160, v157
	v_mov_b32_e32 v161, v158
	v_mov_b32_e32 v157, v159
	v_pk_add_f32 v[156:157], v[160:161], v[156:157]
	s_nop 0
	v_add_f32_e32 v0, v156, v157
	v_fmamk_f32 v0, v0, 0x3b800000, v220
	v_cmp_gt_f32_e32 vcc, s69, v0
	v_mul_f32_e32 v143, 0x4b800000, v0
	v_and_or_b32 v156, v150, s13, v154
	v_cndmask_b32_e32 v0, v0, v143, vcc
	v_rsq_f32_e32 v0, v0
	s_mov_b64 s[12:13], 0
	v_mul_f32_e32 v143, 0x45800000, v0
	v_cndmask_b32_e32 v143, v0, v143, vcc
	v_or_b32_e32 v0, v167, v156
	v_mul_f32_e32 v150, v14, v143
	v_cvt_pk_bf16_f32 v157, v150, s0
	v_lshl_add_u64 v[150:151], v[0:1], 1, s[2:3]
	flat_store_short v[150:151], v157
	v_mul_f32_e32 v150, v15, v143
	v_cvt_pk_bf16_f32 v157, v150, s0
	v_or_b32_e32 v150, 0x800, v0
	v_mov_b32_e32 v151, v1
	v_lshl_add_u64 v[150:151], v[150:151], 1, s[2:3]
	flat_store_short v[150:151], v157
	v_mul_f32_e32 v150, v16, v143
	v_cvt_pk_bf16_f32 v157, v150, s0
	v_or_b32_e32 v150, 0x1000, v0
	v_mov_b32_e32 v151, v1
	v_lshl_add_u64 v[150:151], v[150:151], 1, s[2:3]
	flat_store_short v[150:151], v157
	v_mul_f32_e32 v150, v17, v143
	v_cvt_pk_bf16_f32 v157, v150, s0
	v_or_b32_e32 v150, 0x1800, v0
	v_mov_b32_e32 v151, v1
	v_lshl_add_u64 v[150:151], v[150:151], 1, s[2:3]
	flat_store_short v[150:151], v157
	v_mul_f32_e32 v151, v10, v143
	v_or_b32_e32 v150, 0x2000, v0
	v_cvt_pk_bf16_f32 v157, v151, s0
	v_mov_b32_e32 v151, v1
	v_lshl_add_u64 v[150:151], v[150:151], 1, s[2:3]
	flat_store_short v[150:151], v157
	v_mul_f32_e32 v150, v11, v143
	v_cvt_pk_bf16_f32 v157, v150, s0
	v_or_b32_e32 v150, 0x2800, v0
	v_mov_b32_e32 v151, v1
	v_lshl_add_u64 v[150:151], v[150:151], 1, s[2:3]
	flat_store_short v[150:151], v157
	v_mul_f32_e32 v150, v12, v143
	v_cvt_pk_bf16_f32 v157, v150, s0
	v_or_b32_e32 v150, 0x3000, v0
	v_mov_b32_e32 v151, v1
	v_lshl_add_u64 v[150:151], v[150:151], 1, s[2:3]
	flat_store_short v[150:151], v157
	v_mul_f32_e32 v150, v13, v143
	v_or_b32_e32 v0, 0x3800, v0
	v_cvt_pk_bf16_f32 v157, v150, s0
	v_lshl_add_u64 v[150:151], v[0:1], 1, s[2:3]
	flat_store_short v[150:151], v157
	v_or_b32_e32 v0, v176, v156
	v_mul_f32_e32 v150, v6, v143
	v_cvt_pk_bf16_f32 v156, v150, s0
	v_lshl_add_u64 v[150:151], v[0:1], 1, s[2:3]
	flat_store_short v[150:151], v156
	v_mul_f32_e32 v150, v7, v143
	v_cvt_pk_bf16_f32 v156, v150, s0
	v_or_b32_e32 v150, 0x800, v0
	v_mov_b32_e32 v151, v1
	v_lshl_add_u64 v[150:151], v[150:151], 1, s[2:3]
	flat_store_short v[150:151], v156
	v_mul_f32_e32 v150, v8, v143
	v_cvt_pk_bf16_f32 v156, v150, s0
	v_or_b32_e32 v150, 0x1000, v0
	v_mov_b32_e32 v151, v1
	v_lshl_add_u64 v[150:151], v[150:151], 1, s[2:3]
	flat_store_short v[150:151], v156
	v_mul_f32_e32 v150, v9, v143
	v_cvt_pk_bf16_f32 v156, v150, s0
	v_or_b32_e32 v150, 0x1800, v0
	v_mov_b32_e32 v151, v1
	v_lshl_add_u64 v[150:151], v[150:151], 1, s[2:3]
	flat_store_short v[150:151], v156
	v_mul_f32_e32 v151, v2, v143
	v_or_b32_e32 v150, 0x2000, v0
	v_cvt_pk_bf16_f32 v156, v151, s0
	v_mov_b32_e32 v151, v1
	v_lshl_add_u64 v[150:151], v[150:151], 1, s[2:3]
	flat_store_short v[150:151], v156
	v_mul_f32_e32 v150, v3, v143
	v_cvt_pk_bf16_f32 v156, v150, s0
	v_or_b32_e32 v150, 0x2800, v0
	v_mov_b32_e32 v151, v1
	v_lshl_add_u64 v[150:151], v[150:151], 1, s[2:3]
	flat_store_short v[150:151], v156
	v_mul_f32_e32 v150, v4, v143
	v_cvt_pk_bf16_f32 v156, v150, s0
	v_or_b32_e32 v150, 0x3000, v0
	v_mov_b32_e32 v151, v1
	v_lshl_add_u64 v[150:151], v[150:151], 1, s[2:3]
	v_mul_f32_e32 v143, v5, v143
	v_or_b32_e32 v0, 0x3800, v0
	flat_store_short v[150:151], v156
	v_cvt_pk_bf16_f32 v143, v143, s0
	v_lshl_add_u64 v[150:151], v[0:1], 1, s[2:3]
	flat_store_short v[150:151], v143
